# attention tile 0: q loads issued without waiting for the sink load; SSD cumulative-decay stores plain (flushed by the barrier's release)
# baseline (speedup 1.0000x reference)
; #define LAS __attribute__((address_space(3)))
;     ...
; #pragma unroll
;         for (int i = 0; i < 3; ++i) {
;             const int c = tid + 512 * i, kv = c / 768, cc = c - kv * 768, key = (cc >> 3) * 2, d0 = (cc & 7) * 8;
;             const v4u a = __builtin_bit_cast(v4u, v0[i]), b = __builtin_bit_cast(v4u, v1[i]);
;             LAS unsigned* vt = (LAS unsigned*)(VT + kv * 12800 + d0 * 200 + key);
;             vt[0 * 100] = __builtin_amdgcn_perm(b.x, a.x, 0x05040100u); vt[1 * 100] = __builtin_amdgcn_perm(b.x, a.x, 0x07060302u);
;             vt[2 * 100] = __builtin_amdgcn_perm(b.y, a.y, 0x05040100u); vt[3 * 100] = __builtin_amdgcn_perm(b.y, a.y, 0x07060302u);
;             vt[4 * 100] = __builtin_amdgcn_perm(b.z, a.z, 0x05040100u); vt[5 * 100] = __builtin_amdgcn_perm(b.z, a.z, 0x07060302u);
;             vt[6 * 100] = __builtin_amdgcn_perm(b.w, a.w, 0x05040100u); vt[7 * 100] = __builtin_amdgcn_perm(b.w, a.w, 0x07060302u);
;             *(LAS bf16x8*)(KI + (kv * 192 + key) * 72 + d0) = k0[i];
;             *(LAS bf16x8*)(KI + (kv * 192 + key + 1) * 72 + d0) = k1[i];
;         }
;     }
;     __syncthreads();
;     const int r = lane & 31, hi = lane >> 5;
;     const int hq = wave, hkv = wave >> 2;
;     const float L2E = 1.4426950408889634f; const float slope = exp2f(-(float)(hq + 1)) * L2E, sink = sinks[hq] * L2E;
; #pragma unroll 1
;     for (int qt = (part == 1 ? 1 : 0); qt < (part == 0 ? 1 : 2); ++qt) {
;         const int tq = tok0 + 32 * qt + r;
;         bf16x8 qf[4];
;         { unsigned qo = (unsigned)tq * (unsigned)PS + (unsigned)(OQ + hq * 64 + 8 * hi); asm volatile("" : "+v"(qo)); const bf16* qp = PROJ + qo;
; #pragma unroll
;           for (int ks = 0; ks < 4; ++ks) qf[ks] = ldg8(qp + 16 * ks); }
;         const int ql = 32 * qt + r;
;         float m = sink, lh = 0.f;
;         f32x16 O0 = zero16(), O1 = zero16();
.LBB0_348:
	s_or_b64 exec, exec, s[0:1]
	s_movk_i32 s0, 0x190
	v_mad_u32_u24 v56, v1, s0, 0
	v_mul_i32_i24_e32 v57, 0x6400, v50
	v_lshlrev_b32_e32 v58, 1, v51
	s_mov_b32 s0, 0x5040100
	s_mov_b32 s1, 0x7060302
	v_add3_u32 v57, v56, v57, v58
	s_waitcnt vmcnt(1)
	v_perm_b32 v58, v18, v22, s0
	v_perm_b32 v18, v18, v22, s1
	ds_write2_b32 v57, v58, v18 offset1:100
	v_perm_b32 v18, v19, v23, s0
	v_perm_b32 v19, v19, v23, s1
	v_add_u32_e32 v22, 0x200, v57
	ds_write2_b32 v22, v18, v19 offset0:72 offset1:172
	v_perm_b32 v18, v20, v24, s0
	v_perm_b32 v19, v20, v24, s1
	v_add_u32_e32 v20, 0x400, v57
	ds_write2_b32 v20, v18, v19 offset0:144 offset1:244
	v_perm_b32 v18, v21, v25, s0
	v_perm_b32 v19, v21, v25, s1
	v_add_u32_e32 v20, 0x800, v57
	s_movk_i32 s4, 0xc0
	ds_write2_b32 v20, v18, v19 offset0:88 offset1:188
	v_mad_i32_i24 v18, v50, s4, v51
	s_movk_i32 s5, 0x90
	v_mul_lo_u32 v18, v18, s5
	v_lshlrev_b32_e32 v1, 1, v1
	v_add3_u32 v18, 0, v18, v1
	ds_write_b128 v18, v[14:17] offset:51200
	s_waitcnt vmcnt(0)
	ds_write_b128 v18, v[10:13] offset:51344
	v_mul_i32_i24_e32 v10, 0x6400, v52
	v_lshlrev_b32_e32 v11, 1, v53
	v_add3_u32 v10, v56, v10, v11
	v_perm_b32 v11, v6, v30, s0
	v_perm_b32 v6, v6, v30, s1
	ds_write2_b32 v10, v11, v6 offset1:100
	v_perm_b32 v6, v7, v31, s0
	v_perm_b32 v7, v7, v31, s1
	v_add_u32_e32 v11, 0x200, v10
	ds_write2_b32 v11, v6, v7 offset0:72 offset1:172
	v_perm_b32 v6, v8, v32, s0
	v_perm_b32 v7, v8, v32, s1
	v_add_u32_e32 v8, 0x400, v10
	ds_write2_b32 v8, v6, v7 offset0:144 offset1:244
	v_perm_b32 v6, v9, v33, s0
	v_perm_b32 v7, v9, v33, s1
	v_add_u32_e32 v8, 0x800, v10
	ds_write2_b32 v8, v6, v7 offset0:88 offset1:188
	v_mad_i32_i24 v6, v52, s4, v53
	v_mul_lo_u32 v6, v6, s5
	v_add3_u32 v6, 0, v6, v1
	ds_write_b128 v6, v[26:29] offset:51200
	ds_write_b128 v6, v[2:5] offset:51344
	v_mul_i32_i24_e32 v2, 0x6400, v54
	v_lshlrev_b32_e32 v3, 1, v55
	v_add3_u32 v2, v56, v2, v3
	v_perm_b32 v3, v42, v46, s0
	v_perm_b32 v4, v42, v46, s1
	ds_write2_b32 v2, v3, v4 offset1:100
	v_perm_b32 v3, v43, v47, s0
	v_perm_b32 v4, v43, v47, s1
	v_add_u32_e32 v5, 0x200, v2
	ds_write2_b32 v5, v3, v4 offset0:72 offset1:172
	v_perm_b32 v3, v44, v48, s0
	v_perm_b32 v4, v44, v48, s1
	v_add_u32_e32 v5, 0x400, v2
	ds_write2_b32 v5, v3, v4 offset0:144 offset1:244
	v_perm_b32 v3, v45, v49, s0
	v_perm_b32 v4, v45, v49, s1
	v_add_u32_e32 v2, 0x800, v2
	ds_write2_b32 v2, v3, v4 offset0:88 offset1:188
	v_mad_i32_i24 v2, v54, s4, v55
	v_mul_lo_u32 v2, v2, s5
	v_add3_u32 v1, 0, v2, v1
	s_add_i32 s0, s95, 1
	ds_write_b128 v1, v[38:41] offset:51200
	ds_write_b128 v1, v[34:37] offset:51344
	v_cvt_f32_u32_e32 v1, s0
	s_mov_b32 s0, 0x42fc0000
	v_readlane_b32 s12, v235, 0
	v_readlane_b32 s18, v235, 6
	v_cmp_lt_f32_e32 vcc, s0, v1
	s_and_b64 s[0:1], vcc, exec
	s_cselect_b32 s0, 0xffffffc0, 0
	s_lshl_b32 s1, s95, 2
	v_mov_b32_e32 v3, s1
	v_readlane_b32 s19, v235, 7
	s_waitcnt lgkmcnt(0)
	s_barrier
	v_mov_b32_e32 v2, 0x42800000
	v_cndmask_b32_e32 v2, 0, v2, vcc
	s_nop 0
	global_load_dword v69, v3, s[18:19]
	v_sub_f32_e32 v1, v2, v1
	v_exp_f32_e32 v1, v1
	v_and_b32_e32 v67, 31, v208
	v_or_b32_e32 v66, s8, v67
	s_lshr_b32 s4, s92, 8
	s_and_b32 s8, s92, 0xffffffc0
	v_ldexp_f32 v1, v1, s0
	v_ashrrev_i32_e32 v4, 5, v208
	s_cmpk_gt_u32 s10, 0x7f
	s_mul_i32 s0, s4, 0x6400
	v_lshlrev_b32_e32 v2, 3, v4
	s_cselect_b64 s[10:11], -1, 0
	s_add_i32 s0, s0, 0
	v_mul_f32_e32 v75, 0x3fb8aa3b, v1
	v_readlane_b32 s13, v235, 1
	v_readlane_b32 s14, v235, 2
	v_readlane_b32 s15, v235, 3
	v_readlane_b32 s16, v235, 4
	v_lshlrev_b32_e32 v68, 2, v4
	v_or_b32_e32 v72, 0x80, v67
	s_movk_i32 s13, 0x80
	v_mul_f32_e32 v76, 0, v75
	v_mov_b32_e32 v78, v75
	v_mov_b32_e32 v79, v75
	v_mov_b32_e32 v77, v75
	s_mov_b32 s14, s3
	v_sub_u32_e32 v114, v67, v68
	s_mov_b32 s12, 0x3e38aa3b
	s_mov_b32 s15, 0xf149f2ca
	v_mov_b32_e32 v116, 0xf149f2ca
	v_mov_b32_e32 v94, 0x3e38aa3b
	v_mov_b32_e32 v117, v68
	s_mov_b32 s16, 0
	v_mov_b32_e32 v5, v71
	v_mov_b32_e32 v6, v71
	v_mov_b32_e32 v7, v71
	v_mov_b32_e32 v8, v71
	v_mov_b32_e32 v9, v71
	v_mov_b32_e32 v10, v71
	v_mov_b32_e32 v11, v71
	v_mov_b32_e32 v12, v71
	v_mov_b32_e32 v13, v71
	v_mov_b32_e32 v14, v71
	v_mov_b32_e32 v15, v71
	v_mov_b32_e32 v16, v71
	v_mov_b32_e32 v17, v71
	v_mov_b32_e32 v18, 0
	v_mov_b32_e32 v19, v71
	v_mov_b32_e32 v20, v71
	v_mov_b32_e32 v21, v71
	v_mov_b32_e32 v22, v71
	v_mov_b32_e32 v23, v71
	v_mov_b32_e32 v24, v71
	v_mov_b32_e32 v25, v71
	v_mov_b32_e32 v26, v71
	v_mov_b32_e32 v27, v71
	v_mov_b32_e32 v28, v71
	v_mov_b32_e32 v29, v71
	v_mov_b32_e32 v30, v71
	v_mov_b32_e32 v31, v71
	v_mov_b32_e32 v32, v71
	v_mov_b32_e32 v33, v71
	v_readlane_b32 s17, v235, 5
	v_readlane_b32 s20, v235, 8
	v_readlane_b32 s21, v235, 9
	v_readlane_b32 s22, v235, 10
	v_readlane_b32 s23, v235, 11
	v_readlane_b32 s24, v235, 12
	v_readlane_b32 s25, v235, 13
	v_readlane_b32 s26, v235, 14
	v_readlane_b32 s27, v235, 15
	v_mul_u32_u24_e32 v3, 0x190, v67
	v_add3_u32 v73, s0, v3, v2
	s_movk_i32 s0, 0x900
	v_mul_lo_u32 v1, v66, s0
	v_add3_u32 v70, v2, s8, v1
	s_mov_b32 s0, 2.0
	v_lshl_add_u64 v[2:3], v[70:71], 1, s[80:81]
	global_load_dwordx4 v[50:53], v[2:3], off
	global_load_dwordx4 v[54:57], v[2:3], off offset:32
	global_load_dwordx4 v[58:61], v[2:3], off offset:64
	global_load_dwordx4 v[62:65], v[2:3], off offset:96
	v_mov_b32_e32 v2, v75
	s_mov_b32 s1, 0x40400000
	v_pk_mul_f32 v[80:81], v[2:3], s[0:1] op_sel_hi:[0,1]
	s_mov_b32 s0, 0x41000000
	s_mov_b32 s1, 0x41100000
	v_pk_mul_f32 v[82:83], v[2:3], s[0:1] op_sel_hi:[0,1]
	s_mov_b32 s0, 0x41200000
	s_mov_b32 s1, 0x41300000
	v_pk_mul_f32 v[84:85], v[2:3], s[0:1] op_sel_hi:[0,1]
	s_mov_b32 s0, 0x41800000
	s_mov_b32 s1, 0x41880000
	v_pk_mul_f32 v[86:87], v[2:3], s[0:1] op_sel_hi:[0,1]
	s_mov_b32 s0, 0x41900000
	s_mov_b32 s1, 0x41980000
	v_pk_mul_f32 v[88:89], v[2:3], s[0:1] op_sel_hi:[0,1]
	s_mov_b32 s0, 0x41c00000
	s_mov_b32 s1, 0x41c80000
	v_pk_mul_f32 v[90:91], v[2:3], s[0:1] op_sel_hi:[0,1]
	s_mov_b32 s0, 0x41d00000
	v_mbcnt_lo_u32_b32 v1, -1, 0
	s_mov_b32 s1, 0x41d80000
	v_mbcnt_hi_u32_b32 v1, -1, v1
	v_pk_mul_f32 v[92:93], v[2:3], s[0:1] op_sel_hi:[0,1]
	v_and_b32_e32 v3, 64, v1
	v_xor_b32_e32 v2, 32, v1
	v_add_u32_e32 v3, 64, v3
	v_cmp_lt_i32_e32 vcc, v2, v3
	s_mul_i32 s0, s4, 0x6c00
	v_lshlrev_b32_e32 v3, 4, v4
	v_cndmask_b32_e32 v1, v1, v2, vcc
	v_mov_b32_e32 v2, s0
	v_mad_u32_u24 v2, v67, s5, v2
	v_add3_u32 v2, v2, v3, 0
	v_lshlrev_b32_e32 v70, 2, v1
	v_mov_b32_e32 v1, v72
	v_add_u32_e32 v115, 0xc800, v2
	s_waitcnt vmcnt(4)
	v_mul_f32_e32 v69, 0x3fb8aa3b, v69
	v_mov_b32_e32 v118, v69
	v_mov_b32_e32 v2, 0
	v_mov_b32_e32 v3, v71
	v_mov_b32_e32 v4, v71
